# v3 + scan-phase unit remap: ret/lru units co-reside with ssd CUs instead of rwkv CUs (balances the scan phase pole)
# speedup vs baseline: 1.0199x; 1.0191x over previous
; __device__ __forceinline__ void run_phase(CP p, int ph, char* smem_full) {
;     ...
;     case 3: {
;       for (int u = vb; u < 320; u += NVB) {
;         if (u < 128) { for (int rr_ = 0; rr_ < ((SCAN_REP >> 0) & 1) + 1; ++rr_) rwkv_scan_unit(p, u, smem); }
;         else if (u < 256) { for (int rr_ = 0; rr_ < ((SCAN_REP >> 1) & 1) + 1; ++rr_) ssd_scan_unit(p, l, u - 128, smem); }
;         else if (u < 272) ret_mfma_unit(p, l, u - 256, smem);
;         else if (u < 288) { }
;         else if (u < 320) { for (int rr_ = 0; rr_ < ((SCAN_REP >> 3) & 1) + 1; ++rr_) lru_scan_unit(p, u - 288, smem); }
;       }
;       {
;         const int nwork = NVB > 320 ? NVB - 320 : NVB;
;         const int wk = NVB > 320 ? vb - 320 : vb;
;         const int ngu = 16 * 44;
;         if (wk >= 0) {
.LBB0_391:
	s_andn2_b64 vcc, exec, s[2:3]
	s_cbranch_vccnz .LBB0_649
	s_cmpk_eq_i32 s46, 0x100
	s_cbranch_scc0 .Lmap_done
	s_cmpk_lt_i32 s54, 0x100
	s_cbranch_scc1 .Lmap_done
	s_sub_i32 s0, s54, 0x100
	s_cmpk_lt_i32 s0, 0x70
	s_cbranch_scc0 .Lmap_a
	s_add_i32 s54, s0, 0x140
	s_branch .Lmap_done
.Lmap_a:
	s_cmpk_lt_i32 s0, 0x80
	s_cbranch_scc0 .Lmap_b
	s_movk_i32 s54, 0x110
	s_branch .Lmap_done
.Lmap_b:
	s_cmpk_lt_i32 s0, 0x90
	s_cbranch_scc0 .Lmap_c
	s_add_i32 s54, s0, 0x80
	s_branch .Lmap_done
.Lmap_c:
	s_cmpk_lt_i32 s0, 0xb0
	s_cbranch_scc0 .Lmap_d
	s_add_i32 s54, s0, 0x90
	s_branch .Lmap_done
.Lmap_d:
	s_add_i32 s54, s0, 0x100
.Lmap_done:
	s_cmpk_gt_i32 s54, 0x13f
	s_cbranch_scc1 .LBB0_586
	s_add_u32 s82, s92, 0xe360800
	s_addc_u32 s83, s93, 0
	s_add_u32 s86, s92, 0x7a90c00
	s_addc_u32 s87, s93, 0
	v_readlane_b32 s0, v253, 63
	s_add_u32 s42, s92, 0x84000
	v_readlane_b32 s1, v254, 0
	s_addc_u32 s43, s93, 0
	s_load_dwordx4 s[8:11], s[0:1], 0x58
	s_add_u32 s90, s92, 0x7a90e00
	s_addc_u32 s91, s93, 0
	s_add_u32 s88, s92, 0xfbd1000
	s_addc_u32 s94, s93, 0
	s_waitcnt lgkmcnt(0)
	v_writelane_b32 v254, s8, 14
	s_add_u32 s44, s92, 0xcb30800
	s_addc_u32 s45, s93, 0
	v_writelane_b32 v254, s9, 15
	v_writelane_b32 v254, s10, 16
	s_add_u32 s30, s92, 0x7a90a00
	v_writelane_b32 v254, s11, 17
	s_addc_u32 s31, s93, 0
	s_add_i32 s36, s63, 0xb00
	s_lshl_b32 s37, s54, 4
	s_add_i32 s56, s63, 0x600
	s_mov_b32 s57, s54
	s_branch .LBB0_395
